# dil_tile<2> score section: second K fragment pair requested before the first wait
# baseline (speedup 1.0000x reference)
.LBB0_134:
	s_lshl_b32 s46, s41, 1
	s_cmp_lg_u32 s41, 2
	s_mov_b64 s[0:1], -1
	s_cbranch_scc0 .LBB0_176
	s_lshr_b32 s0, 16, s46
	v_cvt_f32_ubyte0_e32 v0, s0
	v_rcp_iflag_f32_e32 v0, v0
	s_sub_i32 s1, 0, s0
	s_lshr_b32 s4, 0x1000, s46
	s_sub_i32 s2, 12, s46
	v_mul_f32_e32 v0, 0x4f7ffffe, v0
	v_cvt_u32_f32_e32 v0, v0
	s_add_i32 s3, s4, -1
	v_lshlrev_b64 v[36:37], 1, v[134:135]
	s_add_i32 s4, s4, -8
	v_mul_lo_u32 v2, s1, v0
	v_mul_hi_u32 v2, v0, v2
	v_add_u32_e32 v0, v0, v2
	v_mul_hi_u32 v0, v146, v0
	v_mul_lo_u32 v2, v0, s0
	v_sub_u32_e32 v2, v146, v2
	v_add_u32_e32 v3, 1, v0
	v_cmp_le_u32_e32 vcc, s0, v2
	v_readlane_b32 s1, v255, 33
	v_readlane_b32 s8, v253, 51
	v_cndmask_b32_e32 v0, v0, v3, vcc
	v_subrev_u32_e32 v3, s0, v2
	v_cndmask_b32_e32 v2, v2, v3, vcc
	v_add_u32_e32 v3, 1, v0
	v_cmp_le_u32_e32 vcc, s0, v2
	v_readlane_b32 s9, v253, 52
	s_nop 0
	v_cndmask_b32_e32 v0, v0, v3, vcc
	v_xor_b32_e32 v0, v0, v192
	v_sub_u32_e32 v148, v0, v192
	v_mul_lo_u32 v0, v148, s0
	v_sub_u32_e32 v0, v147, v0
	s_lshr_b32 s0, s44, s46
	v_lshl_add_u32 v150, v0, 4, s0
	s_lshl_b32 s0, s41, 2
	v_add_u32_e32 v0, 0xffffff80, v150
	s_add_i32 s0, s1, s0
	v_or_b32_e32 v6, v0, v153
	s_ashr_i32 s1, s0, 31
	v_ashrrev_i32_e32 v149, 31, v148
	v_add_u32_e32 v60, v6, v152
	s_lshl_b64 s[6:7], s[0:1], 12
	v_lshlrev_b64 v[2:3], s2, v[148:149]
	v_min_i32_e32 v6, s3, v60
	v_lshl_add_u64 v[2:3], v[2:3], 0, s[6:7]
	v_ashrrev_i32_e32 v151, 31, v150
	v_readlane_b32 s6, v255, 39
	v_ashrrev_i32_e32 v7, 31, v6
	v_lshl_add_u64 v[4:5], v[2:3], 0, v[150:151]
	v_lshlrev_b64 v[2:3], 7, v[2:3]
	v_readlane_b32 s7, v255, 40
	v_lshlrev_b64 v[6:7], 6, v[6:7]
	v_cmp_lt_i32_e32 vcc, -1, v60
	v_lshl_add_u64 v[34:35], s[6:7], 0, v[2:3]
	v_lshlrev_b64 v[4:5], 7, v[4:5]
	v_cndmask_b32_e32 v7, 0, v7, vcc
	v_cndmask_b32_e32 v6, 0, v6, vcc
	v_lshl_add_u64 v[6:7], v[6:7], 1, v[34:35]
	v_lshl_add_u64 v[50:51], v[142:143], 0, v[4:5]
	v_lshl_add_u64 v[6:7], v[6:7], 0, v[36:37]
	flat_load_dwordx4 v[2:5], v[50:51]
	flat_load_dwordx4 v[26:29], v[6:7]
	v_add_u32_e32 v10, 4, v60
	v_min_i32_e32 v8, s3, v10
	v_ashrrev_i32_e32 v9, 31, v8
	v_lshlrev_b64 v[8:9], 6, v[8:9]
	v_cmp_lt_i32_e32 vcc, -1, v10
	v_add_u32_e32 v38, v150, v134
	v_add_u32_e32 v0, v0, v134
	v_cndmask_b32_e32 v9, 0, v9, vcc
	v_cndmask_b32_e32 v8, 0, v8, vcc
	v_lshl_add_u64 v[8:9], v[8:9], 1, v[34:35]
	v_lshl_add_u64 v[8:9], v[8:9], 0, v[36:37]
	flat_load_dwordx4 v[22:25], v[8:9]
	flat_load_dwordx4 v[30:33], v[6:7] offset:64
	flat_load_dwordx4 v[14:17], v[50:51] offset:64
	flat_load_dwordx4 v[18:21], v[8:9] offset:64
	v_add_u32_e32 v8, 0x80, v60
	v_min_i32_e32 v6, s3, v8
	v_ashrrev_i32_e32 v7, 31, v6
	v_lshlrev_b64 v[6:7], 6, v[6:7]
	v_cmp_lt_i32_e32 vcc, -1, v8
	v_min_i32_e32 v39, s4, v38
	v_min_i32_e32 v40, s4, v0
	v_cndmask_b32_e32 v7, 0, v7, vcc
	v_cndmask_b32_e32 v6, 0, v6, vcc
	v_lshl_add_u64 v[6:7], v[6:7], 1, v[34:35]
	v_lshl_add_u64 v[6:7], v[6:7], 0, v[36:37]
	flat_load_dwordx4 v[10:13], v[6:7]
	s_nop 0
	flat_load_dwordx4 v[6:9], v[6:7] offset:64
	v_cmp_lt_i32_e32 vcc, -1, v38
	v_add_u32_e32 v41, 32, v0
	v_add_u32_e32 v42, 64, v0
	v_cndmask_b32_e32 v84, 0, v39, vcc
	v_cmp_lt_i32_e32 vcc, -1, v0
	v_add_u32_e32 v43, 0x60, v0
	v_min_i32_e32 v38, s4, v41
	v_cndmask_b32_e32 v0, 0, v40, vcc
	v_add_u32_e32 v54, 32, v60
	v_cmp_lt_i32_e32 vcc, -1, v41
	v_min_i32_e32 v39, s4, v42
	v_add_u32_e32 v55, 36, v60
	v_cndmask_b32_e32 v68, 0, v38, vcc
	v_cmp_lt_i32_e32 vcc, -1, v42
	v_min_i32_e32 v42, s3, v54
	v_min_i32_e32 v40, s4, v43
	v_add_u32_e32 v58, 64, v60
	v_cndmask_b32_e32 v86, 0, v39, vcc
	v_cmp_lt_i32_e32 vcc, -1, v43
	v_min_i32_e32 v44, s3, v55
	v_ashrrev_i32_e32 v43, 31, v42
	v_cndmask_b32_e32 v85, 0, v40, vcc
	v_min_i32_e32 v46, s3, v58
	v_ashrrev_i32_e32 v45, 31, v44
	v_lshlrev_b64 v[48:49], 6, v[42:43]
	v_cmp_lt_i32_e32 vcc, -1, v54
	v_ashrrev_i32_e32 v47, 31, v46
	v_lshlrev_b64 v[52:53], 6, v[44:45]
	v_cndmask_b32_e32 v57, 0, v49, vcc
	v_cndmask_b32_e32 v56, 0, v48, vcc
	v_cmp_lt_i32_e32 vcc, -1, v55
	v_lshlrev_b64 v[46:47], 6, v[46:47]
	v_add_u32_e32 v48, 0x44, v60
	v_cndmask_b32_e32 v55, 0, v53, vcc
	v_cndmask_b32_e32 v54, 0, v52, vcc
	v_cmp_lt_i32_e32 vcc, -1, v58
	v_add_u32_e32 v61, 0x64, v60
	s_waitcnt vmcnt(0) lgkmcnt(0)
	v_mfma_f32_16x16x32_bf16 v[38:41], v[26:29], v[2:5], 0
	v_cndmask_b32_e32 v52, 0, v46, vcc
	v_min_i32_e32 v46, s3, v48
	v_cndmask_b32_e32 v53, 0, v47, vcc
	v_ashrrev_i32_e32 v47, 31, v46
	v_lshlrev_b64 v[46:47], 6, v[46:47]
	v_cmp_lt_i32_e32 vcc, -1, v48
	v_add_u32_e32 v48, 0x60, v60
	v_add_u32_e32 v60, 0x84, v60
	v_cndmask_b32_e32 v62, 0, v46, vcc
	v_min_i32_e32 v46, s3, v48
	v_cndmask_b32_e32 v63, 0, v47, vcc
	v_ashrrev_i32_e32 v47, 31, v46
	v_lshlrev_b64 v[46:47], 6, v[46:47]
	v_cmp_lt_i32_e32 vcc, -1, v48
	v_cndmask_b32_e32 v64, 0, v46, vcc
	v_min_i32_e32 v46, s3, v61
	v_cndmask_b32_e32 v65, 0, v47, vcc
	v_ashrrev_i32_e32 v47, 31, v46
	v_lshlrev_b64 v[58:59], 6, v[46:47]
	v_cmp_lt_i32_e32 vcc, -1, v61
	v_cndmask_b32_e32 v66, 0, v58, vcc
	v_min_i32_e32 v58, s3, v60
	v_cndmask_b32_e32 v67, 0, v59, vcc
	v_ashrrev_i32_e32 v59, 31, v58
	v_mfma_f32_16x16x32_bf16 v[42:45], v[22:25], v[2:5], 0
	v_lshlrev_b64 v[58:59], 6, v[58:59]
	v_cmp_lt_i32_e32 vcc, -1, v60
	v_sub_u32_e32 v193, 0x7f, v150
	v_mfma_f32_16x16x32_bf16 v[38:41], v[30:33], v[14:17], v[38:41]
	v_cndmask_b32_e32 v59, 0, v59, vcc
	v_cndmask_b32_e32 v58, 0, v58, vcc
	v_cmp_lt_i32_e32 vcc, v221, v223
	v_cmp_gt_i32_e64 s[58:59], v134, v193
	v_cmp_ge_i32_e64 s[60:61], v134, v193
	v_cndmask_b32_e32 v124, v219, v221, vcc
	v_cmp_lt_i32_e32 vcc, v224, v223
	v_mfma_f32_16x16x32_bf16 v[42:45], v[18:21], v[14:17], v[42:45]
	v_cmp_gt_i32_e64 s[62:63], v154, v193
	v_cndmask_b32_e32 v149, v219, v224, vcc
	s_and_b64 vcc, s[48:49], s[58:59]
	v_cndmask_b32_e32 v127, v227, v38, vcc
	s_and_b64 vcc, s[66:67], s[60:61]
	v_cndmask_b32_e32 v128, v227, v39, vcc
	s_and_b64 vcc, s[68:69], s[62:63]
	v_cmp_gt_i32_e64 s[56:57], v155, v193
	v_cndmask_b32_e32 v131, v227, v40, vcc
	s_and_b64 vcc, s[70:71], s[56:57]
	v_cmp_gt_i32_e64 s[54:55], v156, v193
	v_cndmask_b32_e32 v133, v227, v41, vcc
	s_and_b64 vcc, s[74:75], s[54:55]
	v_cmp_gt_i32_e64 s[36:37], v157, v193
	v_cndmask_b32_e32 v130, v227, v42, vcc
	s_and_b64 vcc, s[76:77], s[36:37]
	v_cmp_gt_i32_e64 s[34:35], v158, v193
	v_cndmask_b32_e32 v132, v227, v43, vcc
	s_and_b64 vcc, s[78:79], s[34:35]
	v_cmp_gt_i32_e64 s[30:31], v159, v193
	v_lshl_add_u64 v[38:39], v[58:59], 1, v[34:35]
	v_cndmask_b32_e32 v151, v227, v44, vcc
	s_and_b64 vcc, s[80:81], s[30:31]
	v_lshl_add_u64 v[38:39], v[38:39], 0, v[36:37]
	v_cndmask_b32_e32 v195, v227, v45, vcc
	flat_load_dwordx4 v[42:45], v[38:39]
	s_nop 0
	flat_load_dwordx4 v[38:41], v[38:39] offset:64
	s_waitcnt vmcnt(0) lgkmcnt(0)
	v_mfma_f32_16x16x32_bf16 v[46:49], v[10:13], v[2:5], 0
	s_lshl_b64 s[0:1], s[0:1], 19
	v_lshl_add_u64 v[82:83], v[138:139], 0, s[0:1]
	v_readlane_b32 s0, v253, 43
	v_mfma_f32_16x16x32_bf16 v[46:49], v[6:9], v[14:17], v[46:49]
	v_cmp_gt_i32_e32 vcc, v184, v193
	v_readlane_b32 s1, v253, 44
	s_and_b64 s[0:1], s[0:1], vcc
	v_readlane_b32 s4, v253, 45
	v_readlane_b32 s5, v253, 46
	s_nop 2
	v_cndmask_b32_e64 v122, v227, v46, s[0:1]
	v_cmp_gt_i32_e64 s[0:1], v185, v193
	s_and_b64 s[4:5], s[4:5], s[0:1]
	v_cndmask_b32_e64 v123, v227, v47, s[4:5]
	v_readlane_b32 s4, v253, 47
	v_cmp_gt_i32_e64 s[38:39], v186, v193
	v_readlane_b32 s5, v253, 48
	v_mfma_f32_16x16x32_bf16 v[58:61], v[42:45], v[2:5], 0
	s_and_b64 s[4:5], s[4:5], s[38:39]
	v_readlane_b32 s6, v253, 49
	v_cndmask_b32_e64 v126, v227, v48, s[4:5]
	v_cmp_gt_i32_e64 s[4:5], v187, v193
	v_readlane_b32 s7, v253, 50
	s_and_b64 s[6:7], s[6:7], s[4:5]
	v_mfma_f32_16x16x32_bf16 v[70:73], v[38:41], v[14:17], v[58:61]
	v_cndmask_b32_e64 v194, v227, v49, s[6:7]
	flat_load_dwordx4 v[46:49], v[50:51] offset:2048
	s_nop 0
	flat_load_dwordx4 v[58:61], v[50:51] offset:2112
	v_cmp_gt_i32_e64 s[6:7], v188, v193
	s_and_b64 s[24:25], s[8:9], s[6:7]
	v_readlane_b32 s8, v253, 53
	s_nop 0
	v_cndmask_b32_e64 v198, v227, v70, s[24:25]
	v_cmp_gt_i32_e64 s[24:25], v189, v193
	v_readlane_b32 s9, v253, 54
	s_and_b64 s[26:27], s[8:9], s[24:25]
	v_readlane_b32 s8, v253, 55
	s_waitcnt vmcnt(0) lgkmcnt(0)
	v_mfma_f32_16x16x32_bf16 v[26:29], v[26:29], v[46:49], 0
	v_cndmask_b32_e64 v199, v227, v71, s[26:27]
	v_cmp_gt_i32_e64 s[26:27], v190, v193
	v_readlane_b32 s9, v253, 56
	s_and_b64 s[28:29], s[8:9], s[26:27]
	v_readlane_b32 s8, v253, 57
	v_cndmask_b32_e64 v201, v227, v72, s[28:29]
	v_cmp_gt_i32_e64 s[28:29], v191, v193
	v_readlane_b32 s9, v253, 58
	s_and_b64 s[64:65], s[8:9], s[28:29]
	v_mfma_f32_16x16x32_bf16 v[26:29], v[30:33], v[58:61], v[26:29]
	v_readlane_b32 s8, v253, 59
	v_readlane_b32 s9, v253, 60
	s_and_b64 s[58:59], s[8:9], s[58:59]
	v_readlane_b32 s8, v253, 61
	v_readlane_b32 s9, v253, 62
	s_nop 2
	v_cndmask_b32_e64 v118, v227, v26, s[58:59]
	s_and_b64 s[58:59], s[8:9], s[60:61]
	v_cndmask_b32_e64 v119, v227, v27, s[58:59]
	v_lshl_add_u64 v[26:27], v[56:57], 1, v[34:35]
	v_lshl_add_u64 v[26:27], v[26:27], 0, v[36:37]
	v_mfma_f32_16x16x32_bf16 v[22:25], v[22:25], v[46:49], 0
	flat_load_dwordx4 v[30:33], v[26:27]
	v_readlane_b32 s8, v253, 63
	v_readlane_b32 s9, v255, 0
	v_mfma_f32_16x16x32_bf16 v[108:111], v[18:21], v[58:61], v[22:25]
	flat_load_dwordx4 v[18:21], v[26:27] offset:64
	s_and_b64 s[58:59], s[8:9], s[62:63]
	v_readlane_b32 s8, v255, 1
	s_waitcnt vmcnt(0) lgkmcnt(0)
	v_mfma_f32_16x16x32_bf16 v[22:25], v[30:33], v[2:5], 0
	v_readlane_b32 s9, v255, 2
	s_and_b64 s[56:57], s[8:9], s[56:57]
	v_cndmask_b32_e64 v120, v227, v28, s[58:59]
	v_mfma_f32_16x16x32_bf16 v[206:209], v[18:21], v[14:17], v[22:25]
	v_cndmask_b32_e64 v121, v227, v29, s[56:57]
	v_lshlrev_b32_e32 v87, s2, v148
	v_add_u32_e32 v0, v0, v87
	s_nop 0
	v_lshl_add_u64 v[22:23], v[54:55], 1, v[34:35]
	v_lshl_add_u64 v[50:51], v[22:23], 0, v[36:37]
	flat_load_dwordx4 v[22:25], v[50:51]
	v_mfma_f32_16x16x32_bf16 v[26:29], v[30:33], v[46:49], 0
	flat_load_dwordx4 v[30:33], v[50:51] offset:64
	v_cndmask_b32_e64 v204, v227, v73, s[64:65]
	v_readlane_b32 s2, v255, 5
	v_mfma_f32_16x16x32_bf16 v[98:101], v[18:21], v[58:61], v[26:29]
	v_lshl_add_u64 v[18:19], v[52:53], 1, v[34:35]
	v_lshl_add_u64 v[50:51], v[18:19], 0, v[36:37]
	flat_load_dwordx4 v[18:21], v[50:51]
	s_waitcnt vmcnt(0) lgkmcnt(0)
	v_mfma_f32_16x16x32_bf16 v[26:29], v[22:25], v[2:5], 0
	v_readlane_b32 s3, v255, 6
	s_and_b64 s[36:37], s[2:3], s[36:37]
	v_readlane_b32 s2, v255, 7
	v_mfma_f32_16x16x32_bf16 v[22:25], v[22:25], v[46:49], 0
	v_readlane_b32 s3, v255, 8
	s_and_b64 s[34:35], s[2:3], s[34:35]
	v_readlane_b32 s2, v255, 9
	v_mfma_f32_16x16x32_bf16 v[90:93], v[30:33], v[58:61], v[22:25]
	v_readlane_b32 s3, v255, 10
	v_cndmask_b32_e64 v109, v227, v109, s[36:37]
	v_cmp_gt_i32_e64 s[36:37], v160, v193
	s_nop 0
	v_lshl_add_u64 v[22:23], v[64:65], 1, v[34:35]
	v_mfma_f32_16x16x32_bf16 v[94:97], v[30:33], v[14:17], v[26:29]
	v_cndmask_b32_e64 v110, v227, v110, s[34:35]
	v_cmp_gt_i32_e64 s[34:35], v161, v193
	s_and_b64 s[30:31], s[2:3], s[30:31]
	v_lshl_add_u64 v[26:27], v[62:63], 1, v[34:35]
	v_lshl_add_u64 v[62:63], v[22:23], 0, v[36:37]
	flat_load_dwordx4 v[22:25], v[62:63]
	v_mfma_f32_16x16x32_bf16 v[30:33], v[18:21], v[2:5], 0
	flat_load_dwordx4 v[50:53], v[50:51] offset:64
	v_lshl_add_u64 v[54:55], v[26:27], 0, v[36:37]
	flat_load_dwordx4 v[26:29], v[54:55]
	flat_load_dwordx4 v[104:107], v[62:63] offset:64
	s_waitcnt vmcnt(0) lgkmcnt(0)
	v_mfma_f32_16x16x32_bf16 v[78:81], v[50:53], v[14:17], v[30:33]
	s_nop 2
	v_lshl_add_u64 v[30:31], v[66:67], 1, v[34:35]
	v_lshl_add_u64 v[34:35], v[30:31], 0, v[36:37]
	flat_load_dwordx4 v[30:33], v[34:35]
	v_mfma_f32_16x16x32_bf16 v[18:21], v[18:21], v[46:49], 0
	flat_load_dwordx4 v[54:57], v[54:55] offset:64
	v_cndmask_b32_e64 v236, v227, v206, s[36:37]
	flat_load_dwordx4 v[34:37], v[34:35] offset:64
	v_mfma_f32_16x16x32_bf16 v[74:77], v[50:53], v[58:61], v[18:21]
	v_ashrrev_i32_e32 v50, 5, v0
	v_ashrrev_i32_e32 v51, 31, v50
	v_lshlrev_b64 v[50:51], 12, v[50:51]
	v_mfma_f32_16x16x32_bf16 v[18:21], v[26:29], v[2:5], 0
	v_and_b32_e32 v0, 31, v0
	v_lshl_add_u64 v[50:51], v[82:83], 0, v[50:51]
	v_lshlrev_b32_e32 v0, 1, v0
	s_waitcnt vmcnt(0) lgkmcnt(0)
	v_mfma_f32_16x16x32_bf16 v[70:73], v[54:57], v[14:17], v[18:21]
	v_lshl_add_u64 v[196:197], v[50:51], 0, v[0:1]
	v_add_u32_e32 v0, v68, v87
	v_cndmask_b32_e64 v237, v227, v207, s[34:35]
	v_mfma_f32_16x16x32_bf16 v[18:21], v[26:29], v[46:49], 0
	v_ashrrev_i32_e32 v26, 5, v0
	v_ashrrev_i32_e32 v27, 31, v26
	v_lshlrev_b64 v[26:27], 12, v[26:27]
	v_and_b32_e32 v0, 31, v0
	v_mfma_f32_16x16x32_bf16 v[66:69], v[54:57], v[58:61], v[18:21]
	v_lshl_add_u64 v[26:27], v[82:83], 0, v[26:27]
	v_lshlrev_b32_e32 v0, 1, v0
	v_lshl_add_u64 v[102:103], v[26:27], 0, v[0:1]
	v_mfma_f32_16x16x32_bf16 v[18:21], v[22:25], v[2:5], 0
	v_add_u32_e32 v0, v86, v87
	v_ashrrev_i32_e32 v26, 5, v0
	v_ashrrev_i32_e32 v27, 31, v26
	v_mfma_f32_16x16x32_bf16 v[62:65], v[104:107], v[14:17], v[18:21]
	v_and_b32_e32 v0, 31, v0
	v_lshlrev_b32_e32 v0, 1, v0
	v_cndmask_b32_e64 v125, v227, v99, s[34:35]
	s_nop 0
	v_lshlrev_b64 v[18:19], 12, v[26:27]
	v_lshl_add_u64 v[26:27], v[82:83], 0, v[18:19]
	v_mfma_f32_16x16x32_bf16 v[18:21], v[22:25], v[46:49], 0
	v_lshl_add_u64 v[112:113], v[26:27], 0, v[0:1]
	v_add_u32_e32 v0, v85, v87
	v_cmp_gt_i32_e64 s[34:35], v164, v193
	v_mfma_f32_16x16x32_bf16 v[54:57], v[104:107], v[58:61], v[18:21]
	v_readlane_b32 s8, v255, 3
	v_cndmask_b32_e64 v94, v227, v94, s[34:35]
	v_readlane_b32 s9, v255, 4
	s_nop 0
	v_ashrrev_i32_e32 v18, 5, v0
	v_mfma_f32_16x16x32_bf16 v[2:5], v[30:33], v[2:5], 0
	v_ashrrev_i32_e32 v19, 31, v18
	v_lshlrev_b64 v[18:19], 12, v[18:19]
	v_and_b32_e32 v0, 31, v0
	v_lshl_add_u64 v[18:19], v[82:83], 0, v[18:19]
	v_lshlrev_b32_e32 v0, 1, v0
	v_mfma_f32_16x16x32_bf16 v[50:53], v[34:37], v[14:17], v[2:5]
	v_lshl_add_u64 v[114:115], v[18:19], 0, v[0:1]
	v_add_u32_e32 v0, v84, v87
	v_ashrrev_i32_e32 v14, 5, v0
	v_mfma_f32_16x16x32_bf16 v[2:5], v[30:33], v[46:49], 0
	v_ashrrev_i32_e32 v15, 31, v14
	v_lshlrev_b64 v[14:15], 12, v[14:15]
	v_and_b32_e32 v0, 31, v0
	v_mfma_f32_16x16x32_bf16 v[104:107], v[34:37], v[58:61], v[2:5]
	v_lshlrev_b32_e32 v0, 1, v0
	s_and_b64 s[54:55], s[8:9], s[54:55]
	v_cndmask_b32_e64 v108, v227, v108, s[54:55]
	s_nop 0
	v_lshl_add_u64 v[2:3], v[82:83], 0, v[14:15]
	v_mfma_f32_16x16x32_bf16 v[10:13], v[10:13], v[46:49], 0
	v_lshl_add_u64 v[116:117], v[2:3], 0, v[0:1]
	v_lshlrev_b32_e32 v0, 2, v124
	v_cndmask_b32_e64 v124, v227, v111, s[30:31]
	v_mfma_f32_16x16x32_bf16 v[14:17], v[42:45], v[46:49], 0
	v_cmp_gt_i32_e64 s[30:31], v162, v193
	v_cndmask_b32_e64 v111, v227, v98, s[36:37]
	v_cmp_gt_i32_e64 s[36:37], v163, v193
	v_mfma_f32_16x16x32_bf16 v[86:89], v[6:9], v[58:61], v[10:13]
	v_cndmask_b32_e64 v238, v227, v208, s[30:31]
	v_cndmask_b32_e64 v98, v227, v209, s[36:37]
	v_cndmask_b32_e64 v129, v227, v100, s[30:31]
	v_mfma_f32_16x16x32_bf16 v[82:85], v[38:41], v[58:61], v[14:17]
	v_max3_f32 v58, v127, s97, v128
	v_max3_f32 v58, v58, v131, v133
	v_max3_f32 v58, v58, v130, v132
	v_max3_f32 v58, v58, v151, v195
	v_max3_f32 v58, v58, v236, v237
	v_cmp_gt_i32_e64 s[30:31], v165, v193
	flat_load_dwordx4 v[18:21], v[196:197]
	flat_load_dwordx4 v[2:5], v[196:197] offset:1024
	flat_load_dwordx4 v[26:29], v[102:103]
	flat_load_dwordx4 v[6:9], v[102:103] offset:1024
	flat_load_dwordx4 v[34:37], v[112:113]
	flat_load_dwordx4 v[10:13], v[112:113] offset:1024
	flat_load_dwordx4 v[42:45], v[114:115]
	flat_load_dwordx4 v[22:25], v[114:115] offset:1024
	flat_load_dwordx4 v[46:49], v[116:117]
	flat_load_dwordx4 v[30:33], v[116:117] offset:1024
	flat_load_dwordx4 v[38:41], v[196:197] offset:2048
	flat_load_dwordx4 v[14:17], v[196:197] offset:3072
	v_max3_f32 v58, v58, v238, v98
	v_cndmask_b32_e64 v95, v227, v95, s[30:31]
	v_cndmask_b32_e64 v196, v227, v101, s[36:37]
	v_cmp_gt_i32_e64 s[36:37], v166, v193
	v_cndmask_b32_e64 v197, v227, v90, s[34:35]
	v_cmp_gt_i32_e64 s[34:35], v167, v193
	v_max3_f32 v58, v58, v94, v95
	v_cndmask_b32_e64 v96, v227, v96, s[36:37]
	v_cndmask_b32_e64 v97, v227, v97, s[34:35]
	v_cndmask_b32_e64 v200, v227, v91, s[30:31]
	v_cmp_gt_i32_e64 s[30:31], v168, v193
	v_cndmask_b32_e64 v202, v227, v92, s[36:37]
	v_cmp_gt_i32_e64 s[36:37], v169, v193
	v_max3_f32 v58, v58, v96, v97
	v_cndmask_b32_e64 v99, v227, v78, s[30:31]
	v_cndmask_b32_e64 v100, v227, v79, s[36:37]
	v_cndmask_b32_e64 v206, v227, v93, s[34:35]
	v_cmp_gt_i32_e64 s[34:35], v170, v193
	v_cndmask_b32_e64 v205, v227, v74, s[30:31]
	v_cmp_gt_i32_e64 s[30:31], v171, v193
	v_max3_f32 v58, v58, v99, v100
	v_cndmask_b32_e64 v101, v227, v80, s[34:35]
	v_cndmask_b32_e64 v239, v227, v81, s[30:31]
	v_cndmask_b32_e64 v207, v227, v75, s[36:37]
	v_cmp_gt_i32_e64 s[36:37], v172, v193
	v_cndmask_b32_e64 v208, v227, v76, s[34:35]
	v_cmp_gt_i32_e64 s[34:35], v173, v193
	v_max3_f32 v58, v58, v101, v239
	v_cndmask_b32_e64 v244, v227, v70, s[36:37]
	v_cndmask_b32_e64 v247, v227, v71, s[34:35]
	v_cndmask_b32_e64 v209, v227, v77, s[30:31]
	v_cmp_gt_i32_e64 s[30:31], v174, v193
	v_cndmask_b32_e64 v210, v227, v66, s[36:37]
	v_cmp_gt_i32_e64 s[36:37], v175, v193
	v_max3_f32 v58, v58, v244, v247
	v_cndmask_b32_e64 v248, v227, v72, s[30:31]
	v_cndmask_b32_e64 v249, v227, v73, s[36:37]
	v_cndmask_b32_e64 v211, v227, v67, s[34:35]
	v_cmp_gt_i32_e64 s[34:35], v176, v193
	v_cndmask_b32_e64 v212, v227, v68, s[30:31]
	v_cmp_gt_i32_e64 s[30:31], v177, v193
	v_max3_f32 v58, v58, v248, v249
	v_cndmask_b32_e64 v242, v227, v62, s[34:35]
	v_cndmask_b32_e64 v250, v227, v63, s[30:31]
	v_cndmask_b32_e64 v214, v227, v69, s[36:37]
	v_cmp_gt_i32_e64 s[36:37], v178, v193
	v_cndmask_b32_e64 v213, v227, v54, s[34:35]
	v_cmp_gt_i32_e64 s[34:35], v179, v193
	v_max3_f32 v58, v58, v242, v250
	v_cndmask_b32_e64 v241, v227, v64, s[36:37]
	v_cndmask_b32_e64 v240, v227, v65, s[34:35]
	v_cndmask_b32_e64 v215, v227, v55, s[30:31]
	v_cmp_gt_i32_e64 s[54:55], v180, v193
	v_cmp_gt_i32_e64 s[30:31], v181, v193
	v_max3_f32 v54, v58, v241, v240
	v_cndmask_b32_e64 v228, v227, v50, s[54:55]
	v_cndmask_b32_e64 v245, v227, v56, s[36:37]
	v_cndmask_b32_e64 v230, v227, v51, s[30:31]
	v_cndmask_b32_e64 v246, v227, v57, s[34:35]
	v_cmp_gt_i32_e64 s[34:35], v182, v193
	v_cmp_gt_i32_e64 s[36:37], v183, v193
	v_max3_f32 v50, v54, v228, v230
	v_cndmask_b32_e64 v231, v227, v52, s[34:35]
	v_cndmask_b32_e64 v203, v227, v104, s[54:55]
	v_cndmask_b32_e64 v104, v227, v53, s[36:37]
	v_max3_f32 v50, v50, v231, v104
	v_max3_f32 v50, v50, v122, v123
	v_max3_f32 v50, v50, v126, v194
	v_max3_f32 v50, v50, v198, v199
	v_max3_f32 v66, v50, v201, v204
	ds_bpermute_b32 v67, v0, v66
	v_lshlrev_b32_e32 v149, 2, v149
	flat_load_dwordx4 v[58:61], v[102:103] offset:2048
	flat_load_dwordx4 v[50:53], v[102:103] offset:3072
	flat_load_dwordx4 v[62:65], v[112:113] offset:2048
	flat_load_dwordx4 v[54:57], v[112:113] offset:3072
	v_readlane_b32 s2, v255, 11
	v_readlane_b32 s3, v255, 12
	s_waitcnt lgkmcnt(0)
	v_max_f32_e32 v67, v67, v67
	v_max_f32_e32 v90, v66, v67
	ds_bpermute_b32 v91, v149, v90
	flat_load_dwordx4 v[74:77], v[114:115] offset:2048
	flat_load_dwordx4 v[66:69], v[114:115] offset:3072
	flat_load_dwordx4 v[78:81], v[116:117] offset:2048
	flat_load_dwordx4 v[70:73], v[116:117] offset:3072
	s_and_b64 vcc, s[2:3], vcc
	v_readlane_b32 s2, v255, 13
	v_readlane_b32 s3, v255, 14
	s_waitcnt lgkmcnt(0)
	v_max_f32_e32 v91, v91, v91
	v_max_f32_e32 v193, v90, v91
	v_sub_f32_e32 v90, v127, v193
	v_exp_f32_e32 v90, v90
	v_sub_f32_e32 v91, v128, v193
	v_exp_f32_e32 v91, v91
	v_sub_f32_e32 v92, v131, v193
	v_exp_f32_e32 v92, v92
	v_sub_f32_e32 v93, v133, v193
	v_exp_f32_e32 v93, v93
	v_sub_f32_e32 v103, v130, v193
	v_add_f32_e32 v102, 0, v90
	v_exp_f32_e32 v103, v103
	v_sub_f32_e32 v112, v132, v193
	v_add_f32_e32 v102, v91, v102
	v_exp_f32_e32 v112, v112
	v_sub_f32_e32 v113, v151, v193
	v_add_f32_e32 v102, v92, v102
	v_exp_f32_e32 v113, v113
	v_add_f32_e32 v102, v93, v102
	v_sub_f32_e32 v114, v195, v193
	v_exp_f32_e32 v114, v114
	v_add_f32_e32 v102, v103, v102
	v_cvt_pk_bf16_f32 v90, v90, v91
	v_cvt_pk_bf16_f32 v91, v92, v93
	v_cvt_pk_bf16_f32 v92, v103, v112
	v_sub_f32_e32 v103, v236, v193
	v_add_f32_e32 v102, v112, v102
	v_exp_f32_e32 v103, v103
	v_sub_f32_e32 v112, v237, v193
	v_add_f32_e32 v102, v113, v102
	v_cvt_pk_bf16_f32 v93, v113, v114
	v_exp_f32_e32 v112, v112
	v_sub_f32_e32 v113, v238, v193
	v_exp_f32_e32 v113, v113
	v_sub_f32_e32 v98, v98, v193
	v_add_f32_e32 v102, v114, v102
	v_exp_f32_e32 v98, v98
	v_sub_f32_e32 v94, v94, v193
	v_add_f32_e32 v102, v103, v102
	v_exp_f32_e32 v114, v94
	v_sub_f32_e32 v94, v95, v193
	v_add_f32_e32 v102, v112, v102
	v_exp_f32_e32 v115, v94
	v_sub_f32_e32 v94, v96, v193
	v_add_f32_e32 v102, v113, v102
	v_exp_f32_e32 v116, v94
	v_sub_f32_e32 v94, v97, v193
	v_add_f32_e32 v102, v98, v102
	v_exp_f32_e32 v97, v94
	v_cvt_pk_bf16_f32 v95, v113, v98
	v_sub_f32_e32 v98, v99, v193
	v_add_f32_e32 v94, v114, v102
	v_exp_f32_e32 v98, v98
	v_sub_f32_e32 v99, v100, v193
	v_add_f32_e32 v94, v115, v94
	v_exp_f32_e32 v99, v99
	v_sub_f32_e32 v100, v101, v193
	v_add_f32_e32 v94, v116, v94
	v_exp_f32_e32 v100, v100
	v_sub_f32_e32 v101, v239, v193
	v_add_f32_e32 v102, v97, v94
	v_cvt_pk_bf16_f32 v94, v103, v112
	v_exp_f32_e32 v101, v101
	v_sub_f32_e32 v103, v244, v193
	v_add_f32_e32 v102, v98, v102
	v_exp_f32_e32 v103, v103
	v_sub_f32_e32 v112, v247, v193
	v_add_f32_e32 v102, v99, v102
	v_exp_f32_e32 v112, v112
	v_sub_f32_e32 v113, v248, v193
	v_cvt_pk_bf16_f32 v96, v114, v115
	v_add_f32_e32 v102, v100, v102
	v_exp_f32_e32 v113, v113
	v_sub_f32_e32 v114, v249, v193
	v_add_f32_e32 v102, v101, v102
	v_exp_f32_e32 v114, v114
	v_add_f32_e32 v102, v103, v102
	v_cvt_pk_bf16_f32 v98, v98, v99
	v_cvt_pk_bf16_f32 v99, v100, v101
	v_cvt_pk_bf16_f32 v100, v103, v112
	v_sub_f32_e32 v103, v242, v193
	v_add_f32_e32 v102, v112, v102
	v_exp_f32_e32 v103, v103
	v_sub_f32_e32 v112, v250, v193
	v_add_f32_e32 v102, v113, v102
	v_cvt_pk_bf16_f32 v101, v113, v114
	v_exp_f32_e32 v112, v112
	v_sub_f32_e32 v113, v241, v193
	v_add_f32_e32 v102, v114, v102
	v_exp_f32_e32 v113, v113
	v_sub_f32_e32 v114, v240, v193
	v_exp_f32_e32 v114, v114
	v_sub_f32_e32 v115, v228, v193
	v_add_f32_e32 v102, v103, v102
	v_exp_f32_e32 v117, v115
	v_sub_f32_e32 v115, v230, v193
	v_add_f32_e32 v102, v112, v102
	v_exp_f32_e32 v127, v115
	v_sub_f32_e32 v115, v231, v193
	v_add_f32_e32 v102, v113, v102
	v_exp_f32_e32 v115, v115
	v_sub_f32_e32 v104, v104, v193
	v_cvt_pk_bf16_f32 v97, v116, v97
	v_add_f32_e32 v102, v114, v102
	v_exp_f32_e32 v116, v104
	v_add_f32_e32 v102, v117, v102
	v_add_f32_e32 v102, v127, v102
	v_add_f32_e32 v102, v115, v102
	v_add_f32_e32 v128, v116, v102
	v_cvt_pk_bf16_f32 v102, v103, v112
	v_sub_f32_e32 v112, v122, v193
	v_exp_f32_e32 v122, v112
	v_sub_f32_e32 v112, v123, v193
	v_cvt_pk_bf16_f32 v104, v117, v127
	v_exp_f32_e32 v127, v112
	v_sub_f32_e32 v112, v126, v193
	v_exp_f32_e32 v117, v112
	v_sub_f32_e32 v112, v194, v193
	v_cvt_pk_bf16_f32 v103, v113, v114
	v_exp_f32_e32 v123, v112
	v_sub_f32_e32 v113, v198, v193
	v_add_f32_e32 v112, v122, v128
	v_exp_f32_e32 v126, v113
	v_sub_f32_e32 v113, v199, v193
	v_add_f32_e32 v112, v127, v112
	v_exp_f32_e32 v128, v113
	v_sub_f32_e32 v113, v201, v193
	v_add_f32_e32 v112, v117, v112
	v_exp_f32_e32 v133, v113
	v_sub_f32_e32 v113, v204, v193
	v_add_f32_e32 v112, v123, v112
	v_exp_f32_e32 v151, v113
	v_add_f32_e32 v112, v126, v112
	v_add_f32_e32 v112, v128, v112
	v_add_f32_e32 v112, v133, v112
	v_add_f32_e32 v131, v151, v112
	v_max3_f32 v112, v118, s97, v119
	v_max3_f32 v112, v112, v120, v121
	v_max3_f32 v112, v112, v108, v109
	v_max3_f32 v112, v112, v110, v124
	v_max3_f32 v112, v112, v111, v125
	v_max3_f32 v112, v112, v129, v196
	v_cndmask_b32_e32 v198, v227, v86, vcc
	s_and_b64 vcc, s[2:3], s[0:1]
	v_readlane_b32 s0, v255, 15
	v_max3_f32 v112, v112, v197, v200
	v_readlane_b32 s1, v255, 16
	v_max3_f32 v112, v112, v202, v206
	v_cndmask_b32_e32 v199, v227, v87, vcc
	s_and_b64 vcc, s[0:1], s[38:39]
	v_readlane_b32 s0, v255, 17
	v_max3_f32 v112, v112, v205, v207
	v_readlane_b32 s1, v255, 18
	v_max3_f32 v112, v112, v208, v209
	v_cndmask_b32_e32 v201, v227, v88, vcc
	s_and_b64 vcc, s[0:1], s[4:5]
	v_readlane_b32 s0, v255, 19
	v_max3_f32 v112, v112, v210, v211
	v_readlane_b32 s1, v255, 20
	v_max3_f32 v112, v112, v212, v214
	v_cndmask_b32_e32 v204, v227, v89, vcc
	s_and_b64 vcc, s[0:1], s[6:7]
	v_readlane_b32 s0, v255, 21
	v_max3_f32 v112, v112, v213, v215
	v_readlane_b32 s1, v255, 22
	v_max3_f32 v113, v112, v245, v246
	v_cndmask_b32_e64 v112, v227, v105, s[30:31]
	v_cndmask_b32_e32 v228, v227, v82, vcc
	s_and_b64 vcc, s[0:1], s[24:25]
	v_readlane_b32 s0, v255, 23
	v_max3_f32 v105, v113, v203, v112
	v_cndmask_b32_e64 v113, v227, v106, s[34:35]
	v_cndmask_b32_e64 v114, v227, v107, s[36:37]
	v_readlane_b32 s1, v255, 24
	v_max3_f32 v105, v105, v113, v114
	v_cndmask_b32_e32 v230, v227, v83, vcc
	s_and_b64 vcc, s[0:1], s[26:27]
	v_readlane_b32 s0, v255, 25
	v_max3_f32 v86, v105, v198, v199
	v_readlane_b32 s1, v255, 26
	v_max3_f32 v86, v86, v201, v204
	v_cndmask_b32_e32 v231, v227, v84, vcc
	s_and_b64 vcc, s[0:1], s[28:29]
	v_max3_f32 v82, v86, v228, v230
	v_cndmask_b32_e32 v236, v227, v85, vcc
	v_max3_f32 v82, v82, v231, v236
	ds_bpermute_b32 v83, v0, v82
	ds_bpermute_b32 v132, v0, v131
	v_cvt_pk_bf16_f32 v105, v115, v116
	v_cvt_pk_bf16_f32 v130, v122, v127
	v_cvt_pk_bf16_f32 v133, v133, v151
	s_waitcnt lgkmcnt(0)
	v_max_f32_e32 v83, v83, v83
	v_max_f32_e32 v82, v82, v83
	ds_bpermute_b32 v83, v149, v82
	v_add_f32_e32 v84, v131, v132
	ds_bpermute_b32 v85, v149, v84
	v_cvt_pk_bf16_f32 v131, v117, v123
	v_cvt_pk_bf16_f32 v132, v126, v128
	s_waitcnt lgkmcnt(0)
	v_max_f32_e32 v83, v83, v83
	v_max_f32_e32 v194, v82, v83
	v_sub_f32_e32 v82, v118, v194
	v_exp_f32_e32 v82, v82
	v_sub_f32_e32 v83, v119, v194
	v_add_f32_e32 v195, v84, v85
	v_exp_f32_e32 v83, v83
	v_sub_f32_e32 v84, v120, v194
	v_exp_f32_e32 v84, v84
	v_sub_f32_e32 v85, v121, v194
	v_exp_f32_e32 v85, v85
	v_sub_f32_e32 v87, v108, v194
	v_add_f32_e32 v86, 0, v82
	v_exp_f32_e32 v87, v87
	v_sub_f32_e32 v88, v109, v194
	v_add_f32_e32 v86, v83, v86
	v_exp_f32_e32 v88, v88
	v_sub_f32_e32 v89, v110, v194
	v_add_f32_e32 v86, v84, v86
	v_exp_f32_e32 v89, v89
	v_sub_f32_e32 v106, v124, v194
	v_add_f32_e32 v86, v85, v86
	v_exp_f32_e32 v106, v106
	v_add_f32_e32 v86, v87, v86
	v_cvt_pk_bf16_f32 v82, v82, v83
	v_cvt_pk_bf16_f32 v83, v84, v85
	v_cvt_pk_bf16_f32 v84, v87, v88
	v_sub_f32_e32 v87, v111, v194
	v_add_f32_e32 v86, v88, v86
	v_exp_f32_e32 v87, v87
	v_sub_f32_e32 v88, v125, v194
	v_add_f32_e32 v86, v89, v86
	v_cvt_pk_bf16_f32 v85, v89, v106
	v_exp_f32_e32 v88, v88
	v_sub_f32_e32 v89, v129, v194
	v_add_f32_e32 v86, v106, v86
	v_exp_f32_e32 v89, v89
	v_sub_f32_e32 v106, v196, v194
	v_exp_f32_e32 v106, v106
	v_sub_f32_e32 v107, v197, v194
	v_add_f32_e32 v86, v87, v86
	v_exp_f32_e32 v107, v107
	v_sub_f32_e32 v108, v200, v194
	v_add_f32_e32 v86, v88, v86
	v_exp_f32_e32 v108, v108
	v_sub_f32_e32 v109, v202, v194
	v_add_f32_e32 v86, v89, v86
	v_exp_f32_e32 v109, v109
	v_sub_f32_e32 v110, v206, v194
	v_add_f32_e32 v86, v106, v86
	v_exp_f32_e32 v110, v110
	v_add_f32_e32 v86, v107, v86
	v_add_f32_e32 v86, v108, v86
	v_add_f32_e32 v86, v109, v86
	v_add_f32_e32 v111, v110, v86
	v_cvt_pk_bf16_f32 v86, v87, v88
	v_cvt_pk_bf16_f32 v87, v89, v106
	v_sub_f32_e32 v106, v205, v194
	v_exp_f32_e32 v106, v106
	v_cvt_pk_bf16_f32 v88, v107, v108
	v_sub_f32_e32 v107, v207, v194
	v_exp_f32_e32 v107, v107
	v_sub_f32_e32 v108, v208, v194
	v_cvt_pk_bf16_f32 v89, v109, v110
	v_exp_f32_e32 v108, v108
	v_sub_f32_e32 v109, v209, v194
	v_exp_f32_e32 v109, v109
	v_add_f32_e32 v110, v106, v111
	v_sub_f32_e32 v111, v210, v194
	v_exp_f32_e32 v111, v111
	v_sub_f32_e32 v115, v211, v194
	v_add_f32_e32 v110, v107, v110
	v_exp_f32_e32 v115, v115
	v_sub_f32_e32 v116, v212, v194
	v_add_f32_e32 v110, v108, v110
	v_exp_f32_e32 v116, v116
	v_sub_f32_e32 v117, v214, v194
	v_add_f32_e32 v110, v109, v110
	v_exp_f32_e32 v117, v117
	v_add_f32_e32 v110, v111, v110
	v_add_f32_e32 v110, v115, v110
	v_add_f32_e32 v110, v116, v110
	v_add_f32_e32 v110, v117, v110
	v_cvt_pk_bf16_f32 v106, v106, v107
	v_cvt_pk_bf16_f32 v107, v108, v109
	v_cvt_pk_bf16_f32 v109, v116, v117
	s_waitcnt vmcnt(0)
	v_mfma_f32_16x16x32_bf16 v[116:119], v[18:21], v[90:93], 0
	v_sub_f32_e32 v108, v213, v194
	v_exp_f32_e32 v122, v108
	v_sub_f32_e32 v108, v215, v194
	v_exp_f32_e32 v123, v108
	v_cvt_pk_bf16_f32 v108, v111, v115
	v_sub_f32_e32 v111, v245, v194
	v_exp_f32_e32 v124, v111
	v_sub_f32_e32 v111, v246, v194
	v_mfma_f32_16x16x32_bf16 v[116:119], v[26:29], v[94:97], v[116:119]
	v_exp_f32_e32 v125, v111
	v_sub_f32_e32 v111, v203, v194
	v_add_f32_e32 v110, v122, v110
	v_exp_f32_e32 v126, v111
	v_add_f32_e32 v110, v123, v110
	v_add_f32_e32 v110, v124, v110
	v_mfma_f32_16x16x32_bf16 v[116:119], v[34:37], v[98:101], v[116:119]
	v_add_f32_e32 v110, v125, v110
	v_add_f32_e32 v115, v126, v110
	v_sub_f32_e32 v110, v112, v194
	v_exp_f32_e32 v127, v110
	v_sub_f32_e32 v110, v113, v194
	v_exp_f32_e32 v128, v110
	v_mfma_f32_16x16x32_bf16 v[110:113], v[42:45], v[102:105], v[116:119]
	v_sub_f32_e32 v114, v114, v194
	v_exp_f32_e32 v129, v114
	v_add_f32_e32 v114, v127, v115
	v_mfma_f32_16x16x32_bf16 v[118:121], v[46:49], v[130:133], v[110:113]
	v_cvt_pk_bf16_f32 v112, v126, v127
	v_cvt_pk_bf16_f32 v111, v124, v125
	v_sub_f32_e32 v127, v204, v194
	s_cmp_lg_u32 s41, 0
	s_cselect_b64 s[4:5], -1, 0
	s_nop 0
	v_add_f32_e32 v110, v128, v114
	v_mfma_f32_16x16x32_bf16 v[114:117], v[2:5], v[90:93], 0
	v_sub_f32_e32 v113, v198, v194
	v_exp_f32_e32 v196, v113
	v_sub_f32_e32 v113, v199, v194
	v_mfma_f32_16x16x32_bf16 v[114:117], v[6:9], v[94:97], v[114:117]
	v_exp_f32_e32 v197, v113
	v_add_f32_e32 v151, v129, v110
	v_cvt_pk_bf16_f32 v110, v122, v123
	v_mfma_f32_16x16x32_bf16 v[114:117], v[10:13], v[98:101], v[114:117]
	v_add_f32_e32 v122, v196, v151
	v_add_f32_e32 v126, v197, v122
	v_sub_f32_e32 v122, v201, v194
	v_mfma_f32_16x16x32_bf16 v[114:117], v[22:25], v[102:105], v[114:117]
	v_exp_f32_e32 v151, v122
	v_exp_f32_e32 v198, v127
	v_sub_f32_e32 v127, v230, v194
	v_mfma_f32_16x16x32_bf16 v[122:125], v[30:33], v[130:133], v[114:117]
	v_exp_f32_e32 v200, v127
	v_sub_f32_e32 v127, v231, v194
	v_add_f32_e32 v126, v151, v126
	s_nop 0
	v_sub_f32_e32 v114, v228, v194
	v_exp_f32_e32 v199, v114
	v_mfma_f32_16x16x32_bf16 v[114:117], v[38:41], v[90:93], 0
	v_exp_f32_e32 v201, v127
	v_sub_f32_e32 v127, v236, v194
	v_add_f32_e32 v126, v198, v126
	v_mfma_f32_16x16x32_bf16 v[90:93], v[14:17], v[90:93], 0
	v_exp_f32_e32 v202, v127
	v_add_f32_e32 v126, v199, v126
	v_add_f32_e32 v126, v200, v126
	v_mfma_f32_16x16x32_bf16 v[114:117], v[58:61], v[94:97], v[114:117]
	v_add_f32_e32 v126, v201, v126
	v_add_f32_e32 v203, v202, v126
	ds_bpermute_b32 v0, v0, v203
	v_mfma_f32_16x16x32_bf16 v[90:93], v[50:53], v[94:97], v[90:93]
	v_cvt_pk_bf16_f32 v113, v128, v129
	s_cmp_eq_u32 s41, 1
	s_cselect_b64 s[0:1], -1, 0
	v_mfma_f32_16x16x32_bf16 v[114:117], v[62:65], v[98:101], v[114:117]
	s_cmp_lg_u32 s41, 1
	v_cndmask_b32_e64 v94, 0, 1, s[0:1]
	s_cselect_b64 s[2:3], -1, 0
	v_mfma_f32_16x16x32_bf16 v[90:93], v[54:57], v[98:101], v[90:93]
	s_and_b64 vcc, exec, s[4:5]
	v_cmp_ne_u32_e64 s[0:1], 1, v94
	v_mfma_f32_16x16x32_bf16 v[114:117], v[74:77], v[102:105], v[114:117]
	v_mfma_f32_16x16x32_bf16 v[90:93], v[66:69], v[102:105], v[90:93]
	v_mfma_f32_16x16x32_bf16 v[126:129], v[78:81], v[130:133], v[114:117]
	v_cvt_pk_bf16_f32 v115, v151, v198
	s_waitcnt lgkmcnt(0)
	v_add_f32_e32 v198, v203, v0
	v_cvt_pk_bf16_f32 v114, v196, v197
	v_cvt_pk_bf16_f32 v116, v199, v200
	ds_bpermute_b32 v199, v149, v198
	v_add_u32_e32 v196, v150, v137
	v_subrev_u32_e32 v197, s44, v148
	v_mfma_f32_16x16x32_bf16 v[90:93], v[70:73], v[130:133], v[90:93]
	v_lshl_add_u32 v200, v196, s46, v197
	v_mul_lo_u32 v0, v200, s73
	v_cvt_pk_bf16_f32 v117, v201, v202
	v_add_u32_e32 v201, 0, v0
	v_ashrrev_i32_e32 v0, 2, v200
	v_add_u32_e32 v202, v0, v136
	s_cbranch_vccz .LBB0_151
	v_lshl_add_u32 v0, v200, 2, 0
	v_add_u32_e32 v203, 0x11000, v0
	ds_read_b32 v94, v203
	v_max_f32_e32 v96, v193, v193
	s_mov_b32 s6, 0xc2fc0000
	v_and_b32_e32 v130, 60, v202
	v_add_u32_e32 v204, 0x11400, v0
	s_waitcnt lgkmcnt(0)
	v_max_f32_e32 v95, v94, v94
	v_max_f32_e32 v205, v95, v96
	v_sub_f32_e32 v94, v94, v205
	v_cmp_gt_f32_e32 vcc, s6, v94
	v_lshl_add_u32 v98, v130, 2, v201
	ds_read_b32 v0, v204
	v_cndmask_b32_e32 v95, 0, v225, vcc
	v_add_f32_e32 v94, v94, v95
	v_exp_f32_e32 v94, v94
	v_cndmask_b32_e32 v95, 0, v226, vcc
	s_mov_b32 s26, 0x15000000
	s_mov_b64 s[8:9], 0x15000600
	v_ldexp_f32 v148, v94, v95
	v_sub_f32_e32 v94, v193, v205
	v_cmp_gt_f32_e32 vcc, s6, v94
	s_nop 1
	v_cndmask_b32_e32 v95, 0, v225, vcc
	v_add_f32_e32 v94, v94, v95
	v_exp_f32_e32 v94, v94
	v_cndmask_b32_e32 v95, 0, v226, vcc
	s_and_b64 vcc, exec, s[0:1]
	v_ldexp_f32 v150, v94, v95
	ds_read_b128 v[94:97], v98
	s_waitcnt lgkmcnt(0)
	v_pk_mul_f32 v[94:95], v[94:95], v[148:149] op_sel_hi:[1,0]
	v_pk_mul_f32 v[96:97], v[96:97], v[148:149] op_sel_hi:[1,0]
	v_pk_fma_f32 v[94:95], v[118:119], v[150:151], v[94:95] op_sel_hi:[1,0,1]
	v_pk_fma_f32 v[96:97], v[120:121], v[150:151], v[96:97] op_sel_hi:[1,0,1]
	s_cbranch_vccnz .LBB0_138
	ds_write_b128 v98, v[94:97]
